# v19 + P0 table loops each assigned to a different block range (SSM tables / pos-embed / casts spread over the grid instead of piling on blocks 0..15)
# baseline (speedup 1.0000x reference)
.LBB0_31:
	s_sub_u32 s32, s2, 96
	s_and_b32 s32, s32, 0xff
	v_lshl_add_u32 v6, s32, 9, v190
	s_movk_i32 s0, 0x2000
	s_lshl_b32 s18, s33, 9
	v_cmp_gt_i32_e32 vcc, s0, v6
	v_ashrrev_i32_e32 v7, 31, v6
	s_and_saveexec_b64 s[8:9], vcc
	s_cbranch_execz .LBB0_38
	v_lshl_add_u64 v[2:3], v[6:7], 3, s[62:63]
	s_mov_b64 s[0:1], 0x100000
	s_ashr_i32 s19, s18, 31
	v_lshl_add_u64 v[2:3], v[2:3], 0, s[0:1]
	s_lshl_b64 s[10:11], s[18:19], 3
	s_mov_b64 s[12:13], 0
	s_mov_b32 s16, 0x3fb8aa3b
	s_mov_b32 s17, 0xc2ce8ed0
	s_mov_b32 s19, 0x42b17218
	v_mov_b32_e32 v1, 0x7f800000
	v_mov_b32_e32 v5, 0
	s_mov_b32 s20, 0x4e441529
	s_mov_b32 s21, 0xa2f9836e
	s_mov_b32 s22, 0x3fc90fda
	s_mov_b32 s23, 0x3f22f983
	s_mov_b32 s24, 0xbfc90fda
	v_mov_b32_e32 v8, 0x3c0881c4
	v_mov_b32_e32 v9, 0xbab64f3b
	s_brev_b32 s25, 1
	s_movk_i32 s27, 0x1f8
	s_movk_i32 s28, 0x1fff
	v_not_b32_e32 v10, 63
	v_not_b32_e32 v11, 31
	v_mov_b32_e32 v12, 0x7fc00000
	v_mov_b32_e32 v13, v6
	s_branch .LBB0_34

.LBB0_38:
	s_or_b64 exec, exec, s[8:9]
	s_mov_b32 s0, 0x10000
	v_or_b32_e32 v135, 4, v160
	v_or_b32_e32 v139, 8, v160
	v_or_b32_e32 v141, 12, v160
	v_or_b32_e32 v143, 16, v160
	v_or_b32_e32 v145, 20, v160
	v_or_b32_e32 v147, 24, v160
	v_or_b32_e32 v149, 28, v160
	v_or_b32_e32 v151, 32, v160
	v_or_b32_e32 v152, 36, v160
	v_or_b32_e32 v153, 40, v160
	v_or_b32_e32 v154, 44, v160
	v_or_b32_e32 v155, 48, v160
	v_or_b32_e32 v156, 52, v160
	v_or_b32_e32 v157, 56, v160
	v_or_b32_e32 v158, 60, v160
	s_sub_u32 s32, s2, 224
	s_and_b32 s32, s32, 0xff
	v_lshl_add_u32 v6, s32, 9, v190
	v_cmp_gt_i32_e32 vcc, s0, v6
	s_and_saveexec_b64 s[10:11], vcc
	s_cbranch_execz .LBB0_47
	v_and_b32_e32 v1, 1, v190
	v_lshl_add_u64 v[2:3], v[6:7], 4, s[62:63]
	s_mov_b64 s[0:1], 0x200000
	s_ashr_i32 s19, s18, 31
	v_cmp_eq_u32_e64 s[4:5], 0, v1
	v_lshl_add_u64 v[8:9], v[2:3], 0, s[0:1]
	s_lshl_b64 s[12:13], s[18:19], 4
	s_mov_b64 s[14:15], 0
	s_mov_b32 s19, 0x3fb8aa3b
	s_mov_b32 s22, 0xc2ce8ed0
	s_mov_b32 s23, 0x42b17218
	v_mov_b32_e32 v11, 0
	s_mov_b32 s24, 0xbfc90fda
	v_mov_b32_e32 v1, 0x3c0881c4
	v_mov_b32_e32 v12, 0xbab64f3b
	s_brev_b32 s25, 1
	s_movk_i32 s27, 0x1f8
	s_mov_b32 s28, 0xffff
	v_mov_b32_e32 v13, 0x7f800000
	v_not_b32_e32 v14, 63
	v_not_b32_e32 v15, 31
	v_mov_b32_e32 v16, 0x7fc00000
	v_mov_b32_e32 v17, v6
	s_branch .LBB0_42

.LBB0_47:
	s_or_b64 exec, exec, s[10:11]
	s_mov_b32 s0, 0x8000
	s_and_b32 s32, s2, 0xff
	v_lshl_add_u32 v6, s32, 9, v190
	v_cmp_gt_i32_e32 vcc, s0, v6
	s_and_saveexec_b64 s[0:1], vcc
	v_readlane_b32 s64, v254, 22
	v_readlane_b32 s66, v254, 24
	v_readlane_b32 s67, v254, 25
	v_readlane_b32 s68, v254, 26
	v_readlane_b32 s69, v254, 27
	v_readlane_b32 s65, v254, 23
	v_readlane_b32 s70, v254, 28
	v_readlane_b32 s71, v254, 29
	v_readlane_b32 s72, v254, 30
	v_readlane_b32 s73, v254, 31
	v_readlane_b32 s74, v254, 32
	v_readlane_b32 s75, v254, 33
	v_readlane_b32 s76, v254, 34
	v_readlane_b32 s77, v254, 35
	v_readlane_b32 s78, v254, 36
	v_readlane_b32 s79, v254, 37
	s_cbranch_execz .LBB0_50
	v_lshl_add_u64 v[2:3], v[6:7], 4, s[62:63]
	s_mov_b64 s[4:5], 0x300000
	s_ashr_i32 s19, s18, 31
	v_lshlrev_b32_e32 v1, 6, v190
	v_lshl_add_u64 v[2:3], v[2:3], 0, s[4:5]
	s_lshl_b64 s[4:5], s[18:19], 4
	v_lshl_add_u32 v1, s32, 15, v1
	s_lshl_b32 s8, s33, 15
	s_mov_b64 s[6:7], 0
	s_movk_i32 s9, 0xffc0
	v_mov_b32_e32 v5, 0
	s_movk_i32 s10, 0x7fff
	v_mov_b32_e32 v8, v6

.LBB0_50:
	s_or_b64 exec, exec, s[0:1]
	s_mov_b32 s0, 0xc000
	s_sub_u32 s32, s2, 112
	s_and_b32 s32, s32, 0xff
	v_lshl_add_u32 v6, s32, 9, v190
	v_cmp_gt_i32_e32 vcc, s0, v6
	s_and_saveexec_b64 s[4:5], vcc
	s_cbranch_execz .LBB0_58
	v_cvt_f32_u32_e32 v2, s18
	v_add_u32_e32 v1, s18, v6
	v_mov_b32_e32 v3, s18
	v_cmp_gt_i32_e32 vcc, s0, v1
	v_rcp_iflag_f32_e32 v2, v2
	s_sub_i32 s6, 0, s18
	v_max_i32_e32 v4, 0xc000, v1
	v_addc_co_u32_e64 v3, s[0:1], v6, v3, vcc
	v_mul_f32_e32 v2, 0x4f7ffffe, v2
	v_cvt_u32_f32_e32 v2, v2
	v_sub_u32_e32 v3, v4, v3
	v_mul_lo_u32 v4, s6, v2
	v_mul_hi_u32 v4, v2, v4
	v_add_u32_e32 v2, v2, v4
	v_mul_hi_u32 v2, v3, v2
	v_mul_lo_u32 v4, v2, s18
	v_sub_u32_e32 v3, v3, v4
	v_add_u32_e32 v5, 1, v2
	v_cmp_le_u32_e64 s[0:1], s18, v3
	v_subrev_u32_e32 v4, s18, v3
	s_mov_b64 s[6:7], -1
	v_cndmask_b32_e64 v2, v2, v5, s[0:1]
	v_cndmask_b32_e64 v3, v3, v4, s[0:1]
	v_add_u32_e32 v4, 1, v2
	v_cmp_le_u32_e64 s[0:1], s18, v3
	s_nop 1
	v_cndmask_b32_e64 v2, v2, v4, s[0:1]
	v_addc_co_u32_e32 v4, vcc, 1, v2, vcc
	v_cmp_lt_u32_e32 vcc, 1, v4
	v_mov_b32_e32 v2, v6
	s_and_saveexec_b64 s[0:1], vcc
	s_cbranch_execz .LBB0_55
	s_add_u32 s6, s62, 0x500000
	s_addc_u32 s7, s63, 0
	v_and_b32_e32 v5, -2, v4
	s_lshl_b32 s10, s33, 10
	v_mov_b32_e32 v2, v6
	s_mov_b32 s11, s10
	s_mov_b64 s[8:9], 0
	v_mov_b32_e32 v3, 0
	v_mov_b32_e32 v8, v5

.LBB0_58:
	s_or_b64 exec, exec, s[4:5]
	s_movk_i32 s0, 0x4000
	s_sub_u32 s32, s2, 64
	s_and_b32 s32, s32, 0xff
	v_lshl_add_u32 v6, s32, 9, v190
	v_cmp_gt_i32_e32 vcc, s0, v6
	s_and_saveexec_b64 s[0:1], vcc
	s_cbranch_execz .LBB0_61
	v_lshlrev_b64 v[2:3], 5, v[6:7]
	v_lshl_add_u64 v[2:3], s[82:83], 0, v[2:3]
	s_ashr_i32 s19, s18, 31
	v_lshl_add_u64 v[4:5], v[6:7], 4, s[62:63]
	s_mov_b64 s[6:7], 0x700000
	v_lshl_add_u64 v[2:3], v[2:3], 0, 16
	s_lshl_b64 s[4:5], s[18:19], 5
	v_lshl_add_u64 v[4:5], v[4:5], 0, s[6:7]
	s_lshl_b64 s[6:7], s[18:19], 4
	s_mov_b64 s[8:9], 0
	s_movk_i32 s10, 0x3fff
	v_mov_b32_e32 v1, v6

.LBB0_61:
	s_or_b64 exec, exec, s[0:1]
	s_mov_b32 s0, 0x14000
	s_sub_u32 s32, s2, 96
	s_and_b32 s32, s32, 0xff
	v_lshl_add_u32 v6, s32, 9, v190
	v_cmp_gt_i32_e32 vcc, s0, v6
	s_and_saveexec_b64 s[8:9], vcc
	s_cbranch_execz .LBB0_76
	v_and_b32_e32 v1, 0x1ff, v190
	v_cvt_f32_u32_e32 v1, v1
	v_mov_b32_e32 v2, 0x461c4000
	s_mov_b32 s0, 0x3f2aaaab
	s_mov_b32 s1, 0x42b17218
	v_mul_f32_e32 v1, 0x3b000000, v1
	v_cmp_eq_f32_e32 vcc, 0, v1
	s_mov_b32 s5, 0x3fb8aa3b
	s_mov_b32 s4, 0x7f800000
	v_cndmask_b32_e64 v14, v2, 1.0, vcc
	v_frexp_mant_f32_e32 v2, v14
	v_cmp_gt_f32_e32 vcc, s0, v2
	s_mov_b32 s0, 0x3f317218
	s_ashr_i32 s19, s18, 31
	v_cndmask_b32_e64 v3, 1.0, 2.0, vcc
	v_mul_f32_e32 v2, v2, v3
	v_add_f32_e32 v5, 1.0, v2
	v_rcp_f32_e32 v12, v5
	v_add_f32_e32 v3, -1.0, v5
	v_sub_f32_e32 v9, v2, v3
	v_add_f32_e32 v3, -1.0, v2
	v_mul_f32_e32 v13, v3, v12
	v_mul_f32_e32 v4, v5, v13
	v_fma_f32 v8, v13, v5, -v4
	v_fmac_f32_e32 v8, v13, v9
	v_add_f32_e32 v2, v4, v8
	v_sub_f32_e32 v5, v3, v2
	v_pk_add_f32 v[10:11], v[2:3], v[4:5] neg_lo:[0,1] neg_hi:[0,1]
	v_mov_b32_e32 v9, v2
	v_pk_add_f32 v[2:3], v[10:11], v[8:9] neg_lo:[0,1] neg_hi:[0,1]
	v_mov_b32_e32 v8, 0x3e91f4c4
	v_add_f32_e32 v2, v2, v3
	v_add_f32_e32 v2, v5, v2
	v_mul_f32_e32 v3, v12, v2
	v_add_f32_e32 v2, v13, v3
	v_sub_f32_e32 v4, v2, v13
	v_sub_f32_e32 v15, v3, v4
	v_mul_f32_e32 v3, v2, v2
	v_fma_f32 v5, v2, v2, -v3
	v_add_f32_e32 v4, v15, v15
	v_fmac_f32_e32 v5, v2, v4
	v_add_f32_e32 v4, v3, v5
	v_fmac_f32_e32 v8, 0x3e76c4e1, v4
	v_fmaak_f32 v8, v4, v8, 0x3ecccdef
	v_sub_f32_e32 v3, v4, v3
	v_sub_f32_e32 v16, v5, v3
	v_mul_f32_e32 v3, v4, v8
	v_fma_f32 v5, v4, v8, -v3
	v_fmac_f32_e32 v5, v16, v8
	v_add_f32_e32 v8, v3, v5
	v_add_f32_e32 v9, 0x3f2aaaaa, v8
	v_sub_f32_e32 v3, v8, v3
	v_sub_f32_e32 v3, v5, v3
	v_add_f32_e32 v5, 0xbf2aaaaa, v9
	v_add_f32_e32 v3, 0x31739010, v3
	v_sub_f32_e32 v5, v8, v5
	v_pk_mul_f32 v[10:11], v[2:3], v[4:5]
	v_pk_add_f32 v[12:13], v[2:3], v[4:5]
	v_fma_f32 v8, v4, v2, -v10
	v_fmac_f32_e32 v8, v4, v15
	v_mov_b32_e32 v11, v13
	v_fmac_f32_e32 v8, v16, v2
	v_pk_add_f32 v[4:5], v[10:11], v[8:9]
	v_ldexp_f32 v16, v15, 1
	v_sub_f32_e32 v3, v4, v10
	v_sub_f32_e32 v3, v8, v3
	v_sub_f32_e32 v8, v9, v5
	v_add_f32_e32 v11, v13, v8
	v_pk_mul_f32 v[8:9], v[4:5], v[4:5] op_sel:[0,1] op_sel_hi:[1,0]
	v_cvt_f64_f32_e32 v[12:13], v14
	v_frexp_exp_i32_f64_e32 v9, v[12:13]
	v_subbrev_co_u32_e32 v9, vcc, 0, v9, vcc
	v_cvt_f32_i32_e32 v9, v9
	v_fma_f32 v10, v4, v5, -v8
	v_fmac_f32_e32 v10, v4, v11
	v_fmac_f32_e32 v10, v3, v5
	v_mul_f32_e32 v4, 0x3f317218, v9
	v_fma_f32 v3, v9, s0, -v4
	v_fmamk_f32 v12, v9, 0xb102e308, v3
	v_ldexp_f32 v13, v2, 1
	v_add_f32_e32 v5, v8, v10
	v_pk_add_f32 v[2:3], v[4:5], v[12:13]
	v_mov_b32_e32 v14, v5
	v_mov_b32_e32 v15, v3
	v_mov_b32_e32 v9, v13
	v_pk_add_f32 v[8:9], v[14:15], v[8:9] neg_lo:[0,1] neg_hi:[0,1]
	v_mov_b32_e32 v11, v5
	v_pk_add_f32 v[8:9], v[10:11], v[8:9] neg_lo:[0,1] neg_hi:[0,1]
	v_mov_b32_e32 v13, v2
	v_add_f32_e32 v5, v16, v8
	v_add_f32_e32 v5, v5, v9
	v_pk_add_f32 v[8:9], v[2:3], v[4:5] neg_lo:[0,1] neg_hi:[0,1]
	v_pk_add_f32 v[10:11], v[2:3], v[4:5]
	v_mov_b32_e32 v4, v5
	v_mov_b32_e32 v9, v11
	v_pk_add_f32 v[14:15], v[12:13], v[8:9] neg_lo:[0,1] neg_hi:[0,1]
	v_pk_add_f32 v[8:9], v[12:13], v[8:9]
	v_mov_b32_e32 v5, v2
	v_pk_add_f32 v[12:13], v[8:9], v[2:3] op_sel:[1,0] op_sel_hi:[0,1] neg_lo:[0,1] neg_hi:[0,1]
	v_pk_add_f32 v[16:17], v[10:11], v[12:13] op_sel_hi:[1,0] neg_lo:[0,1] neg_hi:[0,1]
	v_mov_b32_e32 v10, v11
	v_mov_b32_e32 v11, v9
	v_pk_mov_b32 v[12:13], v[2:3], v[12:13] op_sel:[1,0]
	v_mov_b32_e32 v16, v14
	v_pk_add_f32 v[10:11], v[10:11], v[12:13] neg_lo:[0,1] neg_hi:[0,1]
	v_mov_b32_e32 v15, v9
	v_pk_add_f32 v[2:3], v[4:5], v[10:11] neg_lo:[0,1] neg_hi:[0,1]
	s_movk_i32 s0, 0x204
	v_pk_add_f32 v[4:5], v[16:17], v[2:3]
	s_lshl_b64 s[10:11], s[18:19], 2
	v_pk_add_f32 v[10:11], v[4:5], v[4:5] op_sel:[0,1] op_sel_hi:[1,0]
	s_mov_b64 s[12:13], 0
	v_pk_add_f32 v[8:9], v[8:9], v[10:11] op_sel:[1,0] op_sel_hi:[0,1]
	v_mov_b32_e32 v5, v8
	v_pk_add_f32 v[12:13], v[4:5], v[14:15] neg_lo:[0,1] neg_hi:[0,1]
	v_mov_b32_e32 v3, v10
	v_sub_f32_e32 v4, v4, v12
	v_pk_add_f32 v[2:3], v[2:3], v[12:13] neg_lo:[0,1] neg_hi:[0,1]
	v_sub_f32_e32 v4, v14, v4
	v_add_f32_e32 v2, v2, v4
	v_add_f32_e32 v2, v2, v3
	v_add_f32_e32 v3, v8, v2
	v_sub_f32_e32 v4, v3, v8
	v_sub_f32_e32 v2, v2, v4
	v_mul_f32_e32 v4, v1, v3
	v_fma_f32 v3, v1, v3, -v4
	v_fmac_f32_e32 v3, v1, v2
	v_add_f32_e32 v2, v4, v3
	v_cmp_class_f32_e64 vcc, v4, s0
	v_sub_f32_e32 v5, v2, v4
	v_sub_f32_e32 v3, v3, v5
	v_cndmask_b32_e32 v2, v2, v4, vcc
	v_mov_b32_e32 v4, 0x37000000
	v_cmp_eq_f32_e32 vcc, s1, v2
	s_brev_b32 s19, 18
	s_mov_b32 s22, 0xfe5163ab
	v_cndmask_b32_e32 v4, 0, v4, vcc
	v_sub_f32_e32 v5, v2, v4
	v_mul_f32_e32 v8, 0x3fb8aa3b, v5
	v_fma_f32 v9, v5, s5, -v8
	v_rndne_f32_e32 v10, v8
	v_fmamk_f32 v9, v5, 0x32a5705f, v9
	v_sub_f32_e32 v8, v8, v10
	v_add_f32_e32 v8, v8, v9
	v_exp_f32_e32 v8, v8
	v_cvt_i32_f32_e32 v9, v10
	v_cmp_neq_f32_e64 vcc, |v2|, s4
	s_mov_b32 s5, 0xc2ce8ed0
	s_mov_b32 s23, 0x3c439041
	v_cndmask_b32_e32 v2, 0, v3, vcc
	v_ldexp_f32 v3, v8, v9
	v_cmp_ngt_f32_e32 vcc, s5, v5
	v_add_f32_e32 v2, v4, v2
	v_mov_b32_e32 v4, 0x7f800000
	v_cndmask_b32_e32 v3, 0, v3, vcc
	v_cmp_nlt_f32_e32 vcc, s1, v5
	s_mov_b32 s24, 0xdb629599
	s_mov_b32 s25, 0xf534ddc0
	v_cndmask_b32_e32 v3, v4, v3, vcc
	v_fma_f32 v2, v3, v2, v3
	v_cmp_class_f32_e64 vcc, v3, s0
	s_mov_b32 s27, 0xfc2757d1
	s_mov_b32 s28, 0x4e441529
	v_cndmask_b32_e32 v2, v2, v3, vcc
	v_and_b32_e32 v3, 0x7fffffff, v2
	v_div_scale_f32 v4, s[0:1], v3, v3, 1.0
	v_rcp_f32_e32 v5, v4
	v_div_scale_f32 v3, vcc, 1.0, v3, 1.0
	s_mov_b64 s[0:1], 0x80000
	v_fma_f32 v8, -v4, v5, 1.0
	v_fmac_f32_e32 v5, v8, v5
	v_mul_f32_e32 v8, v3, v5
	v_fma_f32 v9, -v4, v8, v3
	v_fmac_f32_e32 v8, v9, v5
	v_fma_f32 v3, -v4, v8, v3
	v_div_fmas_f32 v3, v3, v5, v8
	v_div_fixup_f32 v2, v3, |v2|, 1.0
	v_cmp_neq_f32_e32 vcc, s4, v1
	v_mov_b32_e32 v5, 0
	s_mov_b32 s29, 0xa2f9836e
	v_cndmask_b32_e32 v1, 0, v2, vcc
	v_lshl_add_u64 v[2:3], v[6:7], 2, s[62:63]
	v_lshl_add_u64 v[2:3], v[2:3], 0, s[0:1]
	s_mov_b32 s30, 0x3fc90fda
	s_mov_b32 s31, 0x3f22f983
	s_mov_b32 s34, 0xbfc90fda
	v_mov_b32_e32 v7, 0x3c0881c4
	v_mov_b32_e32 v8, 0xbab64f3b
	s_brev_b32 s35, 1
	s_movk_i32 s36, 0x1f8
	s_mov_b32 s37, 0x13fff
	v_not_b32_e32 v9, 63
	v_not_b32_e32 v10, 31
	v_mov_b32_e32 v11, 0x7fc00000
	s_branch .LBB0_65
